# norm1/norm2/final phases and mlp2 residual epilogue: serialized load-wait-store chains batched (loads hoisted to fresh VGPRs, vmcnt recounted)
# speedup vs baseline: 1.0180x; 1.0061x over previous
.LBB0_146:
	s_cmpk_gt_i32 s12, 0x1fff
	s_cselect_b64 s[0:1], -1, 0
	s_and_b64 s[0:1], s[14:15], s[0:1]
	v_cndmask_b32_e64 v32, 0, 1, s[0:1]
	v_cmp_ne_u32_e64 s[8:9], 1, v32
	s_andn2_b64 vcc, exec, s[0:1]
	s_cbranch_vccnz .LBB0_153
	s_add_i32 s58, s12, 0xffffe000
	s_lshl_b64 s[0:1], s[58:59], 12
	s_add_u32 s24, s26, s0
	s_addc_u32 s25, s27, s1
	s_add_u32 s22, s24, 0x1000000
	v_lshlrev_b32_e32 v34, 3, v36
	s_addc_u32 s23, s25, 0
	global_load_dwordx2 v[32:33], v34, s[24:25]
	global_load_dwordx2 v[82:83], v34, s[22:23]
	global_load_dwordx4 v[78:81], v[42:43], off
	global_load_dwordx2 v[100:101], v34, s[24:25] offset:512
	v_lshlrev_b32_e32 v102, 3, v44
	global_load_dwordx2 v[104:105], v102, s[22:23]
	global_load_dwordx4 v[106:109], v[42:43], off offset:1024
	global_load_dwordx2 v[110:111], v34, s[24:25] offset:1024
	v_lshlrev_b32_e32 v112, 3, v46
	global_load_dwordx2 v[114:115], v112, s[22:23]
	global_load_dwordx4 v[116:119], v[42:43], off offset:2048
	global_load_dwordx2 v[120:121], v34, s[24:25] offset:1536
	v_lshlrev_b32_e32 v122, 3, v48
	global_load_dwordx2 v[124:125], v122, s[22:23]
	global_load_dwordx4 v[126:129], v[42:43], off offset:3072
	global_load_dwordx2 v[130:131], v34, s[24:25] offset:2048
	v_lshlrev_b32_e32 v132, 3, v50
	global_load_dwordx2 v[134:135], v132, s[22:23]
	global_load_dwordx4 v[136:139], v[52:53], off
	global_load_dwordx2 v[140:141], v34, s[24:25] offset:2560
	v_lshlrev_b32_e32 v142, 3, v54
	global_load_dwordx2 v[188:189], v142, s[22:23]
	global_load_dwordx4 v[190:193], v[56:57], off
	global_load_dwordx2 v[194:195], v34, s[24:25] offset:3072
	v_lshlrev_b32_e32 v196, 3, v58
	global_load_dwordx2 v[198:199], v196, s[22:23]
	global_load_dwordx4 v[200:203], v[60:61], off
	global_load_dwordx2 v[204:205], v34, s[24:25] offset:3584
	v_lshlrev_b32_e32 v206, 3, v62
	global_load_dwordx2 v[208:209], v206, s[22:23]
	global_load_dwordx4 v[210:213], v[64:65], off
	v_lshlrev_b32_e32 v35, 3, v44
	s_waitcnt vmcnt(21)
	v_lshlrev_b32_e32 v84, 16, v32
	v_and_b32_e32 v85, 0xffff0000, v32
	v_lshlrev_b32_e32 v32, 16, v33
	v_and_b32_e32 v33, 0xffff0000, v33
	s_waitcnt vmcnt(22)
	v_lshlrev_b32_e32 v92, 16, v82
	v_and_b32_e32 v93, 0xffff0000, v82
	v_lshlrev_b32_e32 v82, 16, v83
	v_and_b32_e32 v83, 0xffff0000, v83
	v_pk_add_f32 v[32:33], v[32:33], v[82:83]
	v_pk_add_f32 v[84:85], v[84:85], v[92:93]
	s_waitcnt vmcnt(21)
	v_pk_fma_f32 v[30:31], v[80:81], v[32:33], v[30:31]
	v_pk_fma_f32 v[28:29], v[78:79], v[84:85], v[28:29]
	v_lshlrev_b32_e32 v35, 3, v46
	s_waitcnt vmcnt(20)
	v_lshlrev_b32_e32 v84, 16, v100
	v_and_b32_e32 v85, 0xffff0000, v100
	s_waitcnt vmcnt(19)
	v_lshlrev_b32_e32 v92, 16, v104
	v_and_b32_e32 v93, 0xffff0000, v104
	v_lshlrev_b32_e32 v32, 16, v101
	v_and_b32_e32 v33, 0xffff0000, v101
	v_lshlrev_b32_e32 v82, 16, v105
	v_and_b32_e32 v83, 0xffff0000, v105
	v_pk_add_f32 v[84:85], v[84:85], v[92:93]
	v_pk_add_f32 v[32:33], v[32:33], v[82:83]
	s_waitcnt vmcnt(18)
	v_pk_fma_f32 v[24:25], v[106:107], v[84:85], v[24:25]
	v_pk_fma_f32 v[26:27], v[108:109], v[32:33], v[26:27]
	v_mov_b32_e32 v78, v29
	v_mov_b32_e32 v79, v25
	v_mov_b32_e32 v32, v28
	v_mov_b32_e32 v33, v24
	v_pk_mul_f32 v[78:79], v[78:79], v[78:79]
	v_mov_b32_e32 v80, v31
	v_mov_b32_e32 v81, v27
	v_pk_fma_f32 v[32:33], v[32:33], v[32:33], v[78:79]
	v_mov_b32_e32 v78, v30
	v_mov_b32_e32 v79, v26
	v_pk_mul_f32 v[80:81], v[80:81], v[80:81]
	v_pk_fma_f32 v[78:79], v[78:79], v[78:79], v[80:81]
	s_waitcnt vmcnt(17)
	v_lshlrev_b32_e32 v92, 16, v110
	v_pk_add_f32 v[32:33], v[32:33], v[78:79]
	v_and_b32_e32 v93, 0xffff0000, v110
	v_lshlrev_b32_e32 v82, 16, v111
	v_and_b32_e32 v83, 0xffff0000, v111
	v_lshlrev_b32_e32 v35, 3, v48
	v_pk_add_f32 v[32:33], v[32:33], v[32:33] op_sel:[0,1] op_sel_hi:[1,0]
	s_waitcnt vmcnt(16)
	v_lshlrev_b32_e32 v94, 16, v114
	v_and_b32_e32 v95, 0xffff0000, v114
	v_lshlrev_b32_e32 v84, 16, v115
	v_and_b32_e32 v85, 0xffff0000, v115
	v_pk_add_f32 v[82:83], v[82:83], v[84:85]
	v_pk_add_f32 v[84:85], v[92:93], v[94:95]
	s_waitcnt vmcnt(15)
	v_pk_fma_f32 v[22:23], v[118:119], v[82:83], v[22:23]
	v_pk_fma_f32 v[20:21], v[116:117], v[84:85], v[20:21]
	v_pk_mul_f32 v[78:79], v[22:23], v[22:23]
	v_pk_mul_f32 v[80:81], v[20:21], v[20:21]
	v_pk_mov_b32 v[82:83], v[80:81], v[78:79] op_sel:[1,0]
	v_mov_b32_e32 v81, v79
	v_pk_add_f32 v[82:83], v[82:83], v[80:81]
	v_lshlrev_b32_e32 v35, 3, v50
	s_waitcnt vmcnt(14)
	v_lshlrev_b32_e32 v94, 16, v120
	v_and_b32_e32 v95, 0xffff0000, v120
	v_lshlrev_b32_e32 v84, 16, v121
	v_and_b32_e32 v85, 0xffff0000, v121
	s_waitcnt vmcnt(13)
	v_lshlrev_b32_e32 v96, 16, v124
	v_and_b32_e32 v97, 0xffff0000, v124
	v_lshlrev_b32_e32 v92, 16, v125
	v_and_b32_e32 v93, 0xffff0000, v125
	v_pk_add_f32 v[84:85], v[84:85], v[92:93]
	v_pk_add_f32 v[94:95], v[94:95], v[96:97]
	s_waitcnt vmcnt(12)
	v_pk_fma_f32 v[18:19], v[128:129], v[84:85], v[18:19]
	v_pk_fma_f32 v[16:17], v[126:127], v[94:95], v[16:17]
	s_waitcnt vmcnt(11)
	v_lshlrev_b32_e32 v94, 16, v130
	v_and_b32_e32 v95, 0xffff0000, v130
	s_waitcnt vmcnt(10)
	v_lshlrev_b32_e32 v96, 16, v134
	v_and_b32_e32 v97, 0xffff0000, v134
	v_lshlrev_b32_e32 v84, 16, v131
	v_and_b32_e32 v85, 0xffff0000, v131
	v_lshlrev_b32_e32 v92, 16, v135
	v_and_b32_e32 v93, 0xffff0000, v135
	v_pk_add_f32 v[94:95], v[94:95], v[96:97]
	v_pk_add_f32 v[84:85], v[84:85], v[92:93]
	s_waitcnt vmcnt(9)
	v_pk_fma_f32 v[12:13], v[136:137], v[94:95], v[12:13]
	v_pk_fma_f32 v[14:15], v[138:139], v[84:85], v[14:15]
	v_mul_f32_e32 v35, v12, v12
	v_mul_f32_e32 v80, v13, v13
	v_pk_add_f32 v[78:79], v[82:83], v[82:83] op_sel:[0,1] op_sel_hi:[1,0]
	v_mov_b32_e32 v33, v35
	v_mov_b32_e32 v79, v80
	v_pk_add_f32 v[32:33], v[32:33], v[78:79]
	v_mul_f32_e32 v78, v17, v17
	v_mul_f32_e32 v81, v14, v14
	v_pk_fma_f32 v[78:79], v[16:17], v[16:17], v[78:79] op_sel_hi:[1,1,0]
	v_mul_f32_e32 v80, v19, v19
	v_mul_f32_e32 v84, v15, v15
	v_mov_b32_e32 v79, v81
	v_pk_fma_f32 v[80:81], v[18:19], v[18:19], v[80:81] op_sel_hi:[1,1,0]
	v_lshlrev_b32_e32 v35, 3, v54
	v_mov_b32_e32 v81, v84
	v_pk_add_f32 v[78:79], v[78:79], v[80:81]
	s_nop 0
	v_pk_add_f32 v[78:79], v[32:33], v[78:79]
	v_lshlrev_b32_e32 v35, 3, v58
	s_waitcnt vmcnt(8)
	v_lshlrev_b32_e32 v92, 16, v140
	v_and_b32_e32 v93, 0xffff0000, v140
	v_lshlrev_b32_e32 v32, 16, v141
	v_and_b32_e32 v33, 0xffff0000, v141
	s_waitcnt vmcnt(7)
	v_lshlrev_b32_e32 v94, 16, v188
	v_and_b32_e32 v95, 0xffff0000, v188
	v_lshlrev_b32_e32 v84, 16, v189
	v_and_b32_e32 v85, 0xffff0000, v189
	v_pk_add_f32 v[32:33], v[32:33], v[84:85]
	v_pk_add_f32 v[84:85], v[92:93], v[94:95]
	s_waitcnt vmcnt(6)
	v_pk_fma_f32 v[10:11], v[192:193], v[32:33], v[10:11]
	v_pk_fma_f32 v[8:9], v[190:191], v[84:85], v[8:9]
	v_pk_mul_f32 v[32:33], v[10:11], v[10:11]
	v_pk_mul_f32 v[80:81], v[8:9], v[8:9]
	s_nop 0
	v_pk_mov_b32 v[82:83], v[80:81], v[32:33] op_sel:[1,0]
	v_mov_b32_e32 v81, v33
	v_pk_add_f32 v[80:81], v[82:83], v[80:81]
	s_waitcnt vmcnt(5)
	v_lshlrev_b32_e32 v94, 16, v194
	v_and_b32_e32 v95, 0xffff0000, v194
	v_lshlrev_b32_e32 v32, 16, v195
	v_and_b32_e32 v33, 0xffff0000, v195
	s_waitcnt vmcnt(4)
	v_lshlrev_b32_e32 v96, 16, v198
	v_and_b32_e32 v97, 0xffff0000, v198
	v_lshlrev_b32_e32 v92, 16, v199
	v_and_b32_e32 v93, 0xffff0000, v199
	v_pk_add_f32 v[32:33], v[32:33], v[92:93]
	v_pk_add_f32 v[92:93], v[94:95], v[96:97]
	s_waitcnt vmcnt(3)
	v_pk_fma_f32 v[6:7], v[202:203], v[32:33], v[6:7]
	v_pk_fma_f32 v[4:5], v[200:201], v[92:93], v[4:5]
	v_lshlrev_b32_e32 v32, 3, v62
	s_nop 0
	s_waitcnt vmcnt(2)
	v_lshlrev_b32_e32 v92, 16, v204
	v_and_b32_e32 v93, 0xffff0000, v204
	s_waitcnt vmcnt(1)
	v_lshlrev_b32_e32 v94, 16, v208
	v_and_b32_e32 v95, 0xffff0000, v208
	v_lshlrev_b32_e32 v82, 16, v205
	v_and_b32_e32 v83, 0xffff0000, v205
	v_lshlrev_b32_e32 v84, 16, v209
	v_and_b32_e32 v85, 0xffff0000, v209
	v_pk_add_f32 v[92:93], v[92:93], v[94:95]
	v_pk_add_f32 v[82:83], v[82:83], v[84:85]
	s_waitcnt vmcnt(0)
	v_pk_fma_f32 v[0:1], v[210:211], v[92:93], v[0:1]
	v_pk_fma_f32 v[2:3], v[212:213], v[82:83], v[2:3]
	v_mul_f32_e32 v34, v0, v0
	v_pk_add_f32 v[32:33], v[78:79], v[78:79] op_sel:[0,1] op_sel_hi:[1,0]
	v_mul_f32_e32 v82, v1, v1
	v_mov_b32_e32 v33, v34
	v_pk_add_f32 v[34:35], v[80:81], v[80:81] op_sel:[0,1] op_sel_hi:[1,0]
	v_mul_f32_e32 v78, v7, v7
	v_mov_b32_e32 v35, v82
	v_pk_add_f32 v[32:33], v[32:33], v[34:35]
	v_mul_f32_e32 v34, v5, v5
	v_mul_f32_e32 v83, v2, v2
	v_mul_f32_e32 v84, v3, v3
	v_pk_fma_f32 v[34:35], v[4:5], v[4:5], v[34:35] op_sel_hi:[1,1,0]
	v_pk_fma_f32 v[78:79], v[6:7], v[6:7], v[78:79] op_sel_hi:[1,1,0]
	v_mov_b32_e32 v35, v83
	v_mov_b32_e32 v79, v84
	v_pk_add_f32 v[34:35], v[34:35], v[78:79]
	s_nop 0
	v_pk_add_f32 v[32:33], v[32:33], v[34:35]
	s_nop 0
	v_add_f32_e32 v32, v32, v33
	s_and_b64 vcc, exec, s[8:9]
	s_cbranch_vccnz .LBB0_136
	s_branch .LBB0_135

.LBB0_1064:
	s_add_i32 s1, s0, -16
	s_lshr_b32 s1, s1, 4
	s_mulk_i32 s1, 0x3000
	s_addk_i32 s1, 0x3000
	s_cmp_gt_i32 s0, 15
	s_cselect_b32 s58, s1, 0
	s_lshl_b64 s[0:1], s[58:59], 2
	s_add_u32 s0, s29, s0
	v_lshlrev_b64 v[158:159], 12, v[160:161]
	s_addc_u32 s1, s30, s1
	v_mov_b32_e32 v105, v145
	v_lshl_add_u64 v[158:159], s[12:13], 0, v[158:159]
	v_lshl_add_u64 v[156:157], v[104:105], 2, s[0:1]
	v_lshl_add_u64 v[170:171], v[158:159], 0, v[144:145]
	global_load_dwordx4 v[104:107], v[156:157], off offset:16
	global_load_dwordx4 v[108:111], v[156:157], off
	global_load_dwordx4 v[166:169], v[170:171], off
	s_mov_b64 s[0:1], 0x80000
	s_waitcnt vmcnt(0)
	v_lshlrev_b32_e32 v186, 16, v166
	v_and_b32_e32 v187, 0xffff0000, v166
	v_lshlrev_b32_e32 v166, 16, v167
	v_and_b32_e32 v167, 0xffff0000, v167
	v_lshlrev_b32_e32 v188, 16, v168
	v_and_b32_e32 v189, 0xffff0000, v168
	v_lshlrev_b32_e32 v168, 16, v169
	v_and_b32_e32 v169, 0xffff0000, v169
	v_pk_fma_f32 v[134:135], v[134:135], v[110:111], v[166:167]
	v_pk_fma_f32 v[132:133], v[132:133], v[108:109], v[186:187]
	v_pk_fma_f32 v[166:167], v[130:131], v[106:107], v[168:169]
	v_pk_fma_f32 v[130:131], v[128:129], v[104:105], v[188:189]
	v_cvt_pk_bf16_f32 v128, v132, v133
	v_cvt_pk_bf16_f32 v129, v134, v135
	v_cvt_pk_bf16_f32 v130, v130, v131
	v_cvt_pk_bf16_f32 v131, v166, v167
	global_store_dwordx4 v[170:171], v[128:131], off
	s_nop 1
	v_or_b32_e32 v128, 16, v160
	v_ashrrev_i32_e32 v129, 31, v128
	v_lshlrev_b64 v[128:129], 12, v[128:129]
	v_lshl_add_u64 v[128:129], s[12:13], 0, v[128:129]
	v_lshl_add_u64 v[134:135], v[128:129], 0, v[144:145]
	global_load_dwordx4 v[130:133], v[134:135], off
	s_waitcnt vmcnt(0)
	v_lshlrev_b32_e32 v166, 16, v130
	v_and_b32_e32 v167, 0xffff0000, v130
	v_lshlrev_b32_e32 v130, 16, v131
	v_and_b32_e32 v131, 0xffff0000, v131
	v_lshlrev_b32_e32 v168, 16, v132
	v_and_b32_e32 v169, 0xffff0000, v132
	v_lshlrev_b32_e32 v132, 16, v133
	v_and_b32_e32 v133, 0xffff0000, v133
	v_pk_fma_f32 v[126:127], v[126:127], v[110:111], v[130:131]
	v_pk_fma_f32 v[124:125], v[124:125], v[108:109], v[166:167]
	v_pk_fma_f32 v[130:131], v[122:123], v[106:107], v[132:133]
	v_pk_fma_f32 v[122:123], v[120:121], v[104:105], v[168:169]
	v_cvt_pk_bf16_f32 v120, v124, v125
	v_cvt_pk_bf16_f32 v121, v126, v127
	v_cvt_pk_bf16_f32 v122, v122, v123
	v_cvt_pk_bf16_f32 v123, v130, v131
	global_store_dwordx4 v[134:135], v[120:123], off
	s_nop 1
	v_or_b32_e32 v120, 32, v160
	v_ashrrev_i32_e32 v121, 31, v120
	v_lshlrev_b64 v[120:121], 12, v[120:121]
	v_lshl_add_u64 v[120:121], s[12:13], 0, v[120:121]
	v_lshl_add_u64 v[126:127], v[120:121], 0, v[144:145]
	global_load_dwordx4 v[122:125], v[126:127], off
	s_waitcnt vmcnt(0)
	v_lshlrev_b32_e32 v130, 16, v122
	v_and_b32_e32 v131, 0xffff0000, v122
	v_lshlrev_b32_e32 v122, 16, v123
	v_and_b32_e32 v123, 0xffff0000, v123
	v_lshlrev_b32_e32 v132, 16, v124
	v_and_b32_e32 v133, 0xffff0000, v124
	v_lshlrev_b32_e32 v124, 16, v125
	v_and_b32_e32 v125, 0xffff0000, v125
	v_pk_fma_f32 v[118:119], v[118:119], v[110:111], v[122:123]
	v_pk_fma_f32 v[116:117], v[116:117], v[108:109], v[130:131]
	v_pk_fma_f32 v[122:123], v[114:115], v[106:107], v[124:125]
	v_pk_fma_f32 v[114:115], v[112:113], v[104:105], v[132:133]
	v_cvt_pk_bf16_f32 v112, v116, v117
	v_cvt_pk_bf16_f32 v113, v118, v119
	v_cvt_pk_bf16_f32 v114, v114, v115
	v_cvt_pk_bf16_f32 v115, v122, v123
	global_store_dwordx4 v[126:127], v[112:115], off
	s_nop 1
	v_or_b32_e32 v112, 48, v160
	v_ashrrev_i32_e32 v113, 31, v112
	v_lshlrev_b64 v[112:113], 12, v[112:113]
	v_lshl_add_u64 v[112:113], s[12:13], 0, v[112:113]
	v_lshl_add_u64 v[118:119], v[112:113], 0, v[144:145]
	global_load_dwordx4 v[114:117], v[118:119], off
	s_waitcnt vmcnt(0)
	v_lshlrev_b32_e32 v122, 16, v114
	v_and_b32_e32 v123, 0xffff0000, v114
	v_lshlrev_b32_e32 v114, 16, v115
	v_and_b32_e32 v115, 0xffff0000, v115
	v_lshlrev_b32_e32 v124, 16, v116
	v_and_b32_e32 v125, 0xffff0000, v116
	v_lshlrev_b32_e32 v116, 16, v117
	v_and_b32_e32 v117, 0xffff0000, v117
	v_pk_fma_f32 v[102:103], v[102:103], v[110:111], v[114:115]
	v_pk_fma_f32 v[100:101], v[100:101], v[108:109], v[122:123]
	v_pk_fma_f32 v[114:115], v[98:99], v[106:107], v[116:117]
	v_pk_fma_f32 v[98:99], v[96:97], v[104:105], v[124:125]
	v_cvt_pk_bf16_f32 v96, v100, v101
	v_cvt_pk_bf16_f32 v97, v102, v103
	v_cvt_pk_bf16_f32 v98, v98, v99
	v_cvt_pk_bf16_f32 v99, v114, v115
	global_store_dwordx4 v[118:119], v[96:99], off
	s_nop 1
	v_lshl_add_u64 v[96:97], v[158:159], 0, s[0:1]
	v_lshl_add_u64 v[102:103], v[96:97], 0, v[144:145]
	global_load_dwordx4 v[98:101], v[102:103], off
	s_mov_b64 s[0:1], 0x90000
	s_waitcnt vmcnt(0)
	v_lshlrev_b32_e32 v114, 16, v98
	v_and_b32_e32 v115, 0xffff0000, v98
	v_lshlrev_b32_e32 v98, 16, v99
	v_and_b32_e32 v99, 0xffff0000, v99
	v_lshlrev_b32_e32 v116, 16, v100
	v_and_b32_e32 v117, 0xffff0000, v100
	v_lshlrev_b32_e32 v100, 16, v101
	v_and_b32_e32 v101, 0xffff0000, v101
	v_pk_fma_f32 v[94:95], v[94:95], v[110:111], v[98:99]
	v_pk_fma_f32 v[92:93], v[92:93], v[108:109], v[114:115]
	v_pk_fma_f32 v[98:99], v[90:91], v[106:107], v[100:101]
	v_pk_fma_f32 v[90:91], v[88:89], v[104:105], v[116:117]
	v_cvt_pk_bf16_f32 v88, v92, v93
	v_cvt_pk_bf16_f32 v89, v94, v95
	v_cvt_pk_bf16_f32 v90, v90, v91
	v_cvt_pk_bf16_f32 v91, v98, v99
	global_store_dwordx4 v[102:103], v[88:91], off
	s_nop 1
	v_lshl_add_u64 v[88:89], v[158:159], 0, s[0:1]
	v_lshl_add_u64 v[94:95], v[88:89], 0, v[144:145]
	global_load_dwordx4 v[90:93], v[94:95], off
	s_mov_b64 s[0:1], 0xa0000
	s_waitcnt vmcnt(0)
	v_lshlrev_b32_e32 v98, 16, v90
	v_and_b32_e32 v99, 0xffff0000, v90
	v_lshlrev_b32_e32 v90, 16, v91
	v_and_b32_e32 v91, 0xffff0000, v91
	v_lshlrev_b32_e32 v100, 16, v92
	v_and_b32_e32 v101, 0xffff0000, v92
	v_lshlrev_b32_e32 v92, 16, v93
	v_and_b32_e32 v93, 0xffff0000, v93
	v_pk_fma_f32 v[86:87], v[86:87], v[110:111], v[90:91]
	v_pk_fma_f32 v[84:85], v[84:85], v[108:109], v[98:99]
	v_pk_fma_f32 v[90:91], v[82:83], v[106:107], v[92:93]
	v_pk_fma_f32 v[82:83], v[80:81], v[104:105], v[100:101]
	v_cvt_pk_bf16_f32 v80, v84, v85
	v_cvt_pk_bf16_f32 v81, v86, v87
	v_cvt_pk_bf16_f32 v82, v82, v83
	v_cvt_pk_bf16_f32 v83, v90, v91
	global_store_dwordx4 v[94:95], v[80:83], off
	s_nop 1
	v_lshl_add_u64 v[80:81], v[158:159], 0, s[0:1]
	v_lshl_add_u64 v[86:87], v[80:81], 0, v[144:145]
	global_load_dwordx4 v[82:85], v[86:87], off
	s_mov_b64 s[0:1], 0xb0000
	s_waitcnt vmcnt(0)
	v_lshlrev_b32_e32 v90, 16, v82
	v_and_b32_e32 v91, 0xffff0000, v82
	v_lshlrev_b32_e32 v82, 16, v83
	v_and_b32_e32 v83, 0xffff0000, v83
	v_lshlrev_b32_e32 v92, 16, v84
	v_and_b32_e32 v93, 0xffff0000, v84
	v_lshlrev_b32_e32 v84, 16, v85
	v_and_b32_e32 v85, 0xffff0000, v85
	v_pk_fma_f32 v[76:77], v[76:77], v[108:109], v[90:91]
	v_pk_fma_f32 v[78:79], v[78:79], v[110:111], v[82:83]
	v_pk_fma_f32 v[82:83], v[74:75], v[106:107], v[84:85]
	v_pk_fma_f32 v[74:75], v[72:73], v[104:105], v[92:93]
	v_cvt_pk_bf16_f32 v72, v76, v77
	v_lshl_add_u64 v[76:77], v[158:159], 0, s[0:1]
	v_cvt_pk_bf16_f32 v73, v78, v79
	v_cvt_pk_bf16_f32 v74, v74, v75
	v_cvt_pk_bf16_f32 v75, v82, v83
	v_lshl_add_u64 v[78:79], v[76:77], 0, v[144:145]
	global_store_dwordx4 v[86:87], v[72:75], off
	global_load_dwordx4 v[72:75], v[78:79], off
	v_or_b32_e32 v144, 0x100, v144
	s_waitcnt vmcnt(0)
	v_lshlrev_b32_e32 v82, 16, v72
	v_and_b32_e32 v83, 0xffff0000, v72
	v_lshlrev_b32_e32 v72, 16, v73
	v_and_b32_e32 v73, 0xffff0000, v73
	v_lshlrev_b32_e32 v84, 16, v74
	v_and_b32_e32 v85, 0xffff0000, v74
	v_lshlrev_b32_e32 v74, 16, v75
	v_and_b32_e32 v75, 0xffff0000, v75
	v_pk_fma_f32 v[70:71], v[70:71], v[110:111], v[72:73]
	v_pk_fma_f32 v[68:69], v[68:69], v[108:109], v[82:83]
	v_pk_fma_f32 v[72:73], v[66:67], v[106:107], v[74:75]
	v_pk_fma_f32 v[66:67], v[64:65], v[104:105], v[84:85]
	v_cvt_pk_bf16_f32 v64, v68, v69
	v_cvt_pk_bf16_f32 v65, v70, v71
	v_cvt_pk_bf16_f32 v66, v66, v67
	v_cvt_pk_bf16_f32 v67, v72, v73
	global_store_dwordx4 v[78:79], v[64:67], off
	v_lshl_add_u64 v[78:79], v[158:159], 0, v[144:145]
	global_load_dwordx4 v[64:67], v[156:157], off offset:528
	global_load_dwordx4 v[68:71], v[156:157], off offset:512
	global_load_dwordx4 v[72:75], v[78:79], off
	v_lshl_add_u64 v[190:191], v[128:129], 0, v[144:145]
	global_load_dwordx4 v[192:195], v[190:191], off
	v_lshl_add_u64 v[196:197], v[120:121], 0, v[144:145]
	global_load_dwordx4 v[198:201], v[196:197], off
	v_lshl_add_u64 v[202:203], v[112:113], 0, v[144:145]
	global_load_dwordx4 v[204:207], v[202:203], off
	v_lshl_add_u64 v[208:209], v[96:97], 0, v[144:145]
	global_load_dwordx4 v[210:213], v[208:209], off
	v_lshl_add_u64 v[214:215], v[88:89], 0, v[144:145]
	global_load_dwordx4 v[216:219], v[214:215], off
	v_lshl_add_u64 v[220:221], v[80:81], 0, v[144:145]
	global_load_dwordx4 v[222:225], v[220:221], off
	v_lshl_add_u64 v[226:227], v[76:77], 0, v[144:145]
	global_load_dwordx4 v[228:231], v[226:227], off
	s_waitcnt vmcnt(7)
	v_lshlrev_b32_e32 v82, 16, v72
	v_and_b32_e32 v83, 0xffff0000, v72
	v_lshlrev_b32_e32 v72, 16, v73
	v_and_b32_e32 v73, 0xffff0000, v73
	v_lshlrev_b32_e32 v84, 16, v74
	v_and_b32_e32 v85, 0xffff0000, v74
	v_lshlrev_b32_e32 v74, 16, v75
	v_and_b32_e32 v75, 0xffff0000, v75
	v_pk_fma_f32 v[62:63], v[62:63], v[70:71], v[72:73]
	v_pk_fma_f32 v[60:61], v[60:61], v[68:69], v[82:83]
	v_pk_fma_f32 v[72:73], v[58:59], v[66:67], v[74:75]
	v_pk_fma_f32 v[58:59], v[56:57], v[64:65], v[84:85]
	v_cvt_pk_bf16_f32 v56, v60, v61
	v_cvt_pk_bf16_f32 v57, v62, v63
	v_cvt_pk_bf16_f32 v58, v58, v59
	v_cvt_pk_bf16_f32 v59, v72, v73
	v_lshl_add_u64 v[60:61], v[128:129], 0, v[144:145]
	global_store_dwordx4 v[78:79], v[56:59], off
	s_waitcnt vmcnt(7)
	v_lshlrev_b32_e32 v62, 16, v192
	v_and_b32_e32 v63, 0xffff0000, v192
	v_lshlrev_b32_e32 v56, 16, v193
	v_and_b32_e32 v57, 0xffff0000, v193
	v_lshlrev_b32_e32 v72, 16, v194
	v_and_b32_e32 v73, 0xffff0000, v194
	v_lshlrev_b32_e32 v58, 16, v195
	v_and_b32_e32 v59, 0xffff0000, v195
	v_pk_fma_f32 v[54:55], v[54:55], v[70:71], v[56:57]
	v_pk_fma_f32 v[52:53], v[52:53], v[68:69], v[62:63]
	v_pk_fma_f32 v[56:57], v[50:51], v[66:67], v[58:59]
	v_pk_fma_f32 v[50:51], v[48:49], v[64:65], v[72:73]
	v_cvt_pk_bf16_f32 v48, v52, v53
	v_cvt_pk_bf16_f32 v49, v54, v55
	v_cvt_pk_bf16_f32 v50, v50, v51
	v_cvt_pk_bf16_f32 v51, v56, v57
	v_lshl_add_u64 v[52:53], v[120:121], 0, v[144:145]
	global_store_dwordx4 v[60:61], v[48:51], off
	s_waitcnt vmcnt(7)
	v_lshlrev_b32_e32 v54, 16, v198
	v_and_b32_e32 v55, 0xffff0000, v198
	v_lshlrev_b32_e32 v48, 16, v199
	v_and_b32_e32 v49, 0xffff0000, v199
	v_lshlrev_b32_e32 v56, 16, v200
	v_and_b32_e32 v57, 0xffff0000, v200
	v_lshlrev_b32_e32 v50, 16, v201
	v_and_b32_e32 v51, 0xffff0000, v201
	v_pk_fma_f32 v[46:47], v[46:47], v[70:71], v[48:49]
	v_pk_fma_f32 v[44:45], v[44:45], v[68:69], v[54:55]
	v_pk_fma_f32 v[48:49], v[42:43], v[66:67], v[50:51]
	v_pk_fma_f32 v[42:43], v[40:41], v[64:65], v[56:57]
	v_cvt_pk_bf16_f32 v40, v44, v45
	v_cvt_pk_bf16_f32 v41, v46, v47
	v_cvt_pk_bf16_f32 v42, v42, v43
	v_cvt_pk_bf16_f32 v43, v48, v49
	v_lshl_add_u64 v[44:45], v[112:113], 0, v[144:145]
	global_store_dwordx4 v[52:53], v[40:43], off
	s_waitcnt vmcnt(7)
	v_lshlrev_b32_e32 v46, 16, v204
	v_and_b32_e32 v47, 0xffff0000, v204
	v_lshlrev_b32_e32 v40, 16, v205
	v_and_b32_e32 v41, 0xffff0000, v205
	v_lshlrev_b32_e32 v48, 16, v206
	v_and_b32_e32 v49, 0xffff0000, v206
	v_lshlrev_b32_e32 v42, 16, v207
	v_and_b32_e32 v43, 0xffff0000, v207
	v_pk_fma_f32 v[38:39], v[38:39], v[70:71], v[40:41]
	v_pk_fma_f32 v[36:37], v[36:37], v[68:69], v[46:47]
	v_pk_fma_f32 v[40:41], v[34:35], v[66:67], v[42:43]
	v_pk_fma_f32 v[34:35], v[32:33], v[64:65], v[48:49]
	v_cvt_pk_bf16_f32 v32, v36, v37
	v_cvt_pk_bf16_f32 v33, v38, v39
	v_cvt_pk_bf16_f32 v34, v34, v35
	v_cvt_pk_bf16_f32 v35, v40, v41
	v_lshl_add_u64 v[36:37], v[96:97], 0, v[144:145]
	global_store_dwordx4 v[44:45], v[32:35], off
	s_waitcnt vmcnt(7)
	v_lshlrev_b32_e32 v38, 16, v210
	v_and_b32_e32 v39, 0xffff0000, v210
	v_lshlrev_b32_e32 v32, 16, v211
	v_and_b32_e32 v33, 0xffff0000, v211
	v_lshlrev_b32_e32 v40, 16, v212
	v_and_b32_e32 v41, 0xffff0000, v212
	v_lshlrev_b32_e32 v34, 16, v213
	v_and_b32_e32 v35, 0xffff0000, v213
	v_pk_fma_f32 v[30:31], v[30:31], v[70:71], v[32:33]
	v_pk_fma_f32 v[28:29], v[28:29], v[68:69], v[38:39]
	v_pk_fma_f32 v[32:33], v[26:27], v[66:67], v[34:35]
	v_pk_fma_f32 v[26:27], v[24:25], v[64:65], v[40:41]
	v_cvt_pk_bf16_f32 v24, v28, v29
	v_cvt_pk_bf16_f32 v25, v30, v31
	v_cvt_pk_bf16_f32 v26, v26, v27
	v_cvt_pk_bf16_f32 v27, v32, v33
	v_lshl_add_u64 v[28:29], v[88:89], 0, v[144:145]
	global_store_dwordx4 v[36:37], v[24:27], off
	s_waitcnt vmcnt(7)
	v_lshlrev_b32_e32 v30, 16, v216
	v_and_b32_e32 v31, 0xffff0000, v216
	v_lshlrev_b32_e32 v24, 16, v217
	v_and_b32_e32 v25, 0xffff0000, v217
	v_lshlrev_b32_e32 v32, 16, v218
	v_and_b32_e32 v33, 0xffff0000, v218
	v_lshlrev_b32_e32 v26, 16, v219
	v_and_b32_e32 v27, 0xffff0000, v219
	v_pk_fma_f32 v[22:23], v[22:23], v[70:71], v[24:25]
	v_pk_fma_f32 v[20:21], v[20:21], v[68:69], v[30:31]
	v_pk_fma_f32 v[24:25], v[18:19], v[66:67], v[26:27]
	v_pk_fma_f32 v[18:19], v[16:17], v[64:65], v[32:33]
	v_cvt_pk_bf16_f32 v16, v20, v21
	v_cvt_pk_bf16_f32 v17, v22, v23
	v_cvt_pk_bf16_f32 v18, v18, v19
	v_cvt_pk_bf16_f32 v19, v24, v25
	v_lshl_add_u64 v[20:21], v[80:81], 0, v[144:145]
	global_store_dwordx4 v[28:29], v[16:19], off
	s_waitcnt vmcnt(7)
	v_lshlrev_b32_e32 v22, 16, v222
	v_and_b32_e32 v23, 0xffff0000, v222
	v_lshlrev_b32_e32 v16, 16, v223
	v_and_b32_e32 v17, 0xffff0000, v223
	v_lshlrev_b32_e32 v24, 16, v224
	v_and_b32_e32 v25, 0xffff0000, v224
	v_lshlrev_b32_e32 v18, 16, v225
	v_and_b32_e32 v19, 0xffff0000, v225
	v_pk_fma_f32 v[14:15], v[14:15], v[70:71], v[16:17]
	v_pk_fma_f32 v[12:13], v[12:13], v[68:69], v[22:23]
	v_pk_fma_f32 v[16:17], v[10:11], v[66:67], v[18:19]
	v_pk_fma_f32 v[10:11], v[8:9], v[64:65], v[24:25]
	v_cvt_pk_bf16_f32 v8, v12, v13
	v_cvt_pk_bf16_f32 v9, v14, v15
	v_cvt_pk_bf16_f32 v10, v10, v11
	v_cvt_pk_bf16_f32 v11, v16, v17
	v_lshl_add_u64 v[12:13], v[76:77], 0, v[144:145]
	global_store_dwordx4 v[20:21], v[8:11], off
	s_waitcnt vmcnt(7)
	v_lshlrev_b32_e32 v14, 16, v228
	v_and_b32_e32 v15, 0xffff0000, v228
	v_lshlrev_b32_e32 v8, 16, v229
	v_and_b32_e32 v9, 0xffff0000, v229
	v_lshlrev_b32_e32 v16, 16, v230
	v_and_b32_e32 v17, 0xffff0000, v230
	v_lshlrev_b32_e32 v10, 16, v231
	v_and_b32_e32 v11, 0xffff0000, v231
	v_pk_fma_f32 v[6:7], v[6:7], v[70:71], v[8:9]
	v_pk_fma_f32 v[4:5], v[4:5], v[68:69], v[14:15]
	v_pk_fma_f32 v[8:9], v[2:3], v[66:67], v[10:11]
	v_pk_fma_f32 v[2:3], v[0:1], v[64:65], v[16:17]
	v_cvt_pk_bf16_f32 v0, v4, v5
	v_cvt_pk_bf16_f32 v1, v6, v7
	v_cvt_pk_bf16_f32 v2, v2, v3
	v_cvt_pk_bf16_f32 v3, v8, v9
	global_store_dwordx4 v[12:13], v[0:3], off
	s_andn2_b64 vcc, exec, s[18:19]
	s_mov_b64 s[18:19], -1
	s_cbranch_vccnz .LBB0_1055

.LBB0_1123:
	global_load_dwordx4 v[44:47], v[0:1], off
	global_load_dwordx4 v[188:191], v[0:1], off offset:1024
	global_load_dwordx4 v[192:195], v[0:1], off offset:2048
	global_load_dwordx4 v[196:199], v[0:1], off offset:3072
	global_load_dwordx4 v[200:203], v[12:13], off
	global_load_dwordx4 v[204:207], v[14:15], off
	global_load_dwordx4 v[208:211], v[16:17], off
	global_load_dwordx4 v[212:215], v[18:19], off
	ds_bpermute_b32 v48, v68, v83
	s_add_i32 s2, s2, s34
	s_cmpk_lt_i32 s2, 0x3000
	v_lshl_add_u64 v[22:23], v[22:23], 0, s[42:43]
	s_waitcnt lgkmcnt(0)
	v_add_f32_e32 v48, v83, v48
	ds_bpermute_b32 v49, v69, v48
	s_waitcnt lgkmcnt(0)
	v_add_f32_e32 v48, v48, v49
	ds_bpermute_b32 v49, v70, v48
	s_waitcnt lgkmcnt(0)
	v_add_f32_e32 v48, v48, v49
	ds_bpermute_b32 v49, v71, v48
	s_waitcnt lgkmcnt(0)
	v_add_f32_e32 v48, v48, v49
	ds_bpermute_b32 v49, v72, v48
	s_waitcnt lgkmcnt(0)
	v_add_f32_e32 v48, v48, v49
	ds_bpermute_b32 v49, v73, v48
	s_waitcnt lgkmcnt(0)
	v_add_f32_e32 v48, v48, v49
	v_fmamk_f32 v48, v48, 0x3a000000, v82
	v_mul_f32_e32 v49, 0x4b800000, v48
	v_cmp_gt_f32_e32 vcc, s3, v48
	s_nop 1
	v_cndmask_b32_e32 v48, v48, v49, vcc
	v_rsq_f32_e32 v50, v48
	v_add_co_u32_e64 v48, s[0:1], s6, v20
	v_mul_f32_e32 v51, 0x45800000, v50
	v_cndmask_b32_e32 v50, v50, v51, vcc
	v_pk_mul_f32 v[40:41], v[40:41], v[50:51] op_sel_hi:[1,0]
	v_pk_mul_f32 v[42:43], v[42:43], v[50:51] op_sel_hi:[1,0]
	v_addc_co_u32_e64 v49, s[0:1], -1, v21, s[0:1]
	v_pk_mul_f32 v[38:39], v[38:39], v[50:51] op_sel_hi:[1,0]
	v_pk_mul_f32 v[36:37], v[36:37], v[50:51] op_sel_hi:[1,0]
	v_pk_mul_f32 v[34:35], v[34:35], v[50:51] op_sel_hi:[1,0]
	v_pk_mul_f32 v[32:33], v[32:33], v[50:51] op_sel_hi:[1,0]
	v_pk_mul_f32 v[30:31], v[30:31], v[50:51] op_sel_hi:[1,0]
	v_pk_mul_f32 v[28:29], v[28:29], v[50:51] op_sel_hi:[1,0]
	v_pk_mul_f32 v[26:27], v[26:27], v[50:51] op_sel_hi:[1,0]
	v_pk_mul_f32 v[24:25], v[24:25], v[50:51] op_sel_hi:[1,0]
	s_waitcnt vmcnt(7)
	v_pk_mul_f32 v[42:43], v[46:47], v[42:43]
	v_pk_mul_f32 v[40:41], v[44:45], v[40:41]
	global_store_dwordx4 v[48:49], v[40:43], off offset:-3072
	v_pk_mul_f32 v[44:45], v[62:63], v[50:51] op_sel_hi:[1,0]
	v_pk_mul_f32 v[46:47], v[64:65], v[50:51] op_sel_hi:[1,0]
	s_waitcnt vmcnt(7)
	v_pk_mul_f32 v[42:43], v[190:191], v[44:45]
	v_pk_mul_f32 v[40:41], v[188:189], v[46:47]
	global_store_dwordx4 v[48:49], v[40:43], off offset:-2048
	s_waitcnt vmcnt(7)
	v_pk_mul_f32 v[36:37], v[192:193], v[36:37]
	v_pk_mul_f32 v[38:39], v[194:195], v[38:39]
	global_store_dwordx4 v[48:49], v[36:39], off offset:-1024
	s_waitcnt vmcnt(7)
	v_pk_mul_f32 v[32:33], v[196:197], v[32:33]
	v_pk_mul_f32 v[34:35], v[198:199], v[34:35]
	global_store_dwordx4 v[20:21], v[32:35], off offset:-4096
	v_pk_mul_f32 v[36:37], v[54:55], v[50:51] op_sel_hi:[1,0]
	v_pk_mul_f32 v[38:39], v[56:57], v[50:51] op_sel_hi:[1,0]
	s_waitcnt vmcnt(7)
	v_pk_mul_f32 v[34:35], v[202:203], v[36:37]
	v_pk_mul_f32 v[32:33], v[200:201], v[38:39]
	global_store_dwordx4 v[20:21], v[32:35], off offset:-3072
	v_pk_mul_f32 v[36:37], v[60:61], v[50:51] op_sel_hi:[1,0]
	v_pk_mul_f32 v[38:39], v[58:59], v[50:51] op_sel_hi:[1,0]
	s_waitcnt vmcnt(7)
	v_pk_mul_f32 v[34:35], v[206:207], v[36:37]
	v_pk_mul_f32 v[32:33], v[204:205], v[38:39]
	global_store_dwordx4 v[20:21], v[32:35], off offset:-2048
	s_waitcnt vmcnt(7)
	v_pk_mul_f32 v[28:29], v[28:29], v[208:209]
	v_pk_mul_f32 v[30:31], v[30:31], v[210:211]
	global_store_dwordx4 v[20:21], v[28:31], off offset:-1024
	s_waitcnt vmcnt(7)
	v_pk_mul_f32 v[24:25], v[24:25], v[212:213]
	v_pk_mul_f32 v[26:27], v[26:27], v[214:215]
	global_store_dwordx4 v[20:21], v[24:27], off
	v_lshl_add_u64 v[20:21], v[20:21], 0, s[40:41]
	s_cbranch_scc0 .LBB0_1128
